# v80 + nt on the last read of the f32 input rows (P6 layer-0 residual epilogue)
# speedup vs baseline: 1.0003x; 1.0003x over previous
;     __device__ __forceinline__ void operator()(const f32x4 (&acc)[2][2][4][2], const Unit& u, int wr, int wc, int fr, int fq) const {
;     ...
;             for (int n = 0; n < 2; ++n) { gv[bj][n] = *(const f32x4*)(gam + col0 + bj * HALF + 4 * n); bv[bj][n] = *(const f32x4*)(bet + col0 + bj * HALF + 4 * n); }
;         constexpr int MB = (SRCF32 ? 2 : 4) / (EMIT ? 2 : 1);
; #pragma unroll
;         for (int ai = 0; ai < 2; ++ai)
; #pragma unroll
;           for (int mb = 0; mb < 4; mb += MB) { float2 ms[MB]; u32x4 xb[MB][2]; f32x4 xf[MB][2][2];
; #pragma unroll
;             for (int m = 0; m < MB; ++m) { const size_t ro = (size_t)(row0 + ai * HALF + (mb + m) * 16); ms[m] = *(const float2*)(must + ro * 2);
; #pragma unroll
;                 for (int bj = 0; bj < 2; ++bj) { const size_t o = ro * 2048 + col0 + bj * HALF;
;                     if (SRCF32) { xf[m][bj][0] = *(const f32x4*)((const float*)src + o); xf[m][bj][1] = *(const f32x4*)((const float*)src + o + 4); }
;                     else xb[m][bj] = *(const u32x4*)((const bf16_t*)src + o); } }
;             asm volatile("" ::: "memory");
; #pragma unroll
;             for (int m = 0; m < MB; ++m) { const size_t ro = (size_t)(row0 + ai * HALF + (mb + m) * 16); float s = 0.f, q = 0.f;
; #pragma unroll
;                 for (int bj = 0; bj < 2; ++bj) { const size_t o = ro * 2048 + col0 + bj * HALF; f32x4 x0, x1;
;                     if (SRCF32) { x0 = xf[m][bj][0]; x1 = xf[m][bj][1]; }
;                     else { const u32x4 w = xb[m][bj]; x0 = (f32x4){bf_lo(w.x), bf_hi(w.x), bf_lo(w.y), bf_hi(w.y)}; x1 = (f32x4){bf_lo(w.z), bf_hi(w.z), bf_lo(w.w), bf_hi(w.w)}; }
;                     x0 = (x0 - ms[m].x) * ms[m].y * gv[bj][0] + bv[bj][0]; x1 = (x1 - ms[m].x) * ms[m].y * gv[bj][1] + bv[bj][1];
;                     const f32x4 v0 = x0 * alpha + acc[ai][bj][mb + m][0], v1 = x1 * alpha + acc[ai][bj][mb + m][1];
;                     if (EMIT) { s += ((v0[0] + v0[1]) + (v0[2] + v0[3])) + ((v1[0] + v1[1]) + (v1[2] + v1[3]));
;                         q += ((v0[0] * v0[0] + v0[1] * v0[1]) + (v0[2] * v0[2] + v0[3] * v0[3])) + ((v1[0] * v1[0] + v1[1] * v1[1]) + (v1[2] * v1[2] + v1[3] * v1[3])); }
;                     *(u32x4*)(dst + o) = PG8_PACK8(v0, v1); }
;                 if (EMIT) { s = xsum16(s); s = xsum32(s); q = xsum16(q); q = xsum32(q);
.LBB0_870:
	s_lshl_b32 s31, s31, 8
	v_add_u32_e32 v174, s31, v176
	v_lshl_or_b32 v172, s30, 8, v178
	v_ashrrev_i32_e32 v175, 31, v174
	v_ashrrev_i32_e32 v173, 31, v172
	v_lshlrev_b64 v[68:69], 13, v[174:175]
	v_lshlrev_b64 v[66:67], 2, v[172:173]
	v_lshl_add_u64 v[68:69], s[14:15], 0, v[68:69]
	v_lshl_add_u64 v[70:71], v[174:175], 3, s[18:19]
	v_lshl_add_u64 v[68:69], v[68:69], 0, v[66:67]
	global_load_dwordx2 v[200:201], v[70:71], off
	global_load_dwordx4 v[184:187], v[68:69], off nt
	global_load_dwordx4 v[188:191], v[68:69], off offset:16 nt
	global_load_dwordx4 v[192:195], v[68:69], off offset:512 nt
	global_load_dwordx4 v[196:199], v[68:69], off offset:528 nt
	v_lshl_add_u64 v[70:71], s[20:21], 0, v[66:67]
	v_lshl_add_u64 v[82:83], s[22:23], 0, v[66:67]
	global_load_dwordx4 v[74:77], v[82:83], off
	global_load_dwordx4 v[94:97], v[70:71], off
	global_load_dwordx4 v[78:81], v[70:71], off offset:16
	global_load_dwordx4 v[90:93], v[82:83], off offset:16
	global_load_dwordx4 v[66:69], v[82:83], off offset:512
	global_load_dwordx4 v[86:89], v[70:71], off offset:512
	s_nop 0
	global_load_dwordx4 v[70:73], v[70:71], off offset:528
	s_nop 0
	global_load_dwordx4 v[82:85], v[82:83], off offset:528
	v_lshlrev_b64 v[202:203], 12, v[174:175]
	v_lshl_add_u64 v[202:203], s[16:17], 0, v[202:203]
	v_lshl_add_u64 v[202:203], v[172:173], 1, v[202:203]
	s_waitcnt vmcnt(0)
	v_sub_f32_e32 v187, v187, v200
	v_sub_f32_e32 v186, v186, v200
	v_sub_f32_e32 v185, v185, v200
	v_sub_f32_e32 v184, v184, v200
	v_sub_f32_e32 v191, v191, v200
	v_sub_f32_e32 v190, v190, v200
	v_sub_f32_e32 v189, v189, v200
	v_sub_f32_e32 v188, v188, v200
	v_sub_f32_e32 v193, v193, v200
	v_sub_f32_e32 v192, v192, v200
	v_pk_mul_f32 v[184:185], v[200:201], v[184:185] op_sel:[1,0]
	v_pk_mul_f32 v[186:187], v[200:201], v[186:187] op_sel:[1,0]
	v_pk_mul_f32 v[188:189], v[200:201], v[188:189] op_sel:[1,0]
	v_pk_mul_f32 v[190:191], v[200:201], v[190:191] op_sel:[1,0]
	v_sub_f32_e32 v199, v199, v200
	v_sub_f32_e32 v198, v198, v200
	v_sub_f32_e32 v197, v197, v200
	v_sub_f32_e32 v196, v196, v200
	v_pk_mul_f32 v[192:193], v[200:201], v[192:193] op_sel:[1,0]
	v_pk_fma_f32 v[186:187], v[96:97], v[186:187], v[76:77]
	v_pk_fma_f32 v[184:185], v[94:95], v[184:185], v[74:75]
	v_pk_fma_f32 v[190:191], v[80:81], v[190:191], v[92:93]
	v_pk_fma_f32 v[188:189], v[78:79], v[188:189], v[90:91]
	v_sub_f32_e32 v195, v195, v200
	v_sub_f32_e32 v194, v194, v200
	v_pk_mul_f32 v[196:197], v[200:201], v[196:197] op_sel:[1,0]
	v_pk_mul_f32 v[198:199], v[200:201], v[198:199] op_sel:[1,0]
	v_pk_fma_f32 v[192:193], v[86:87], v[192:193], v[66:67]
	v_pk_fma_f32 v[160:161], v[186:187], s[96:97], v[160:161] op_sel_hi:[1,0,1]
	v_pk_fma_f32 v[158:159], v[184:185], s[96:97], v[158:159] op_sel_hi:[1,0,1]
	v_pk_fma_f32 v[156:157], v[190:191], s[96:97], v[156:157] op_sel_hi:[1,0,1]
	v_pk_fma_f32 v[154:155], v[188:189], s[96:97], v[154:155] op_sel_hi:[1,0,1]
	v_pk_mul_f32 v[194:195], v[200:201], v[194:195] op_sel:[1,0]
	v_pk_fma_f32 v[198:199], v[72:73], v[198:199], v[84:85]
	v_pk_fma_f32 v[196:197], v[70:71], v[196:197], v[82:83]
	v_pk_fma_f32 v[150:151], v[192:193], s[96:97], v[150:151] op_sel_hi:[1,0,1]
	v_mul_f32_e32 v189, v159, v159
	v_mul_f32_e32 v190, v161, v161
	v_mul_f32_e32 v191, v155, v155
	v_mul_f32_e32 v192, v157, v157
	v_pk_fma_f32 v[194:195], v[88:89], v[194:195], v[68:69]
	v_pk_fma_f32 v[184:185], v[198:199], s[96:97], v[148:149] op_sel_hi:[1,0,1]
	v_pk_fma_f32 v[186:187], v[196:197], s[96:97], v[146:147] op_sel_hi:[1,0,1]
	v_cvt_pk_bf16_f32 v146, v158, v159
	v_cvt_pk_bf16_f32 v147, v160, v161
	v_cvt_pk_bf16_f32 v148, v154, v155
	v_cvt_pk_bf16_f32 v149, v156, v157
	v_fmac_f32_e32 v189, v158, v158
	v_fmac_f32_e32 v190, v160, v160
	v_fmac_f32_e32 v191, v154, v154
	v_fmac_f32_e32 v192, v156, v156
	v_pk_fma_f32 v[152:153], v[194:195], s[96:97], v[152:153] op_sel_hi:[1,0,1]
	v_add_f32_e32 v1, v158, v159
	v_add_f32_e32 v175, v160, v161
	v_add_f32_e32 v183, v154, v155
	v_add_f32_e32 v188, v156, v157
	global_store_dwordx4 v[202:203], v[146:149], off
	v_add_f32_e32 v155, v150, v151
	v_add_f32_e32 v1, v1, v175
	v_add_f32_e32 v146, v189, v190
	v_add_f32_e32 v147, v191, v192
	v_add_f32_e32 v157, v183, v188
	v_add_f32_e32 v146, v146, v147
	v_add_f32_e32 v147, v152, v153
	v_add_f32_e32 v148, v186, v187
	v_add_f32_e32 v149, v184, v185
	v_add_f32_e32 v1, v1, v157
	v_add_f32_e32 v147, v155, v147
	v_add_f32_e32 v148, v148, v149
	v_add_f32_e32 v1, 0, v1
	v_add_f32_e32 v147, v147, v148
	v_add_f32_e32 v1, v147, v1
	v_mul_f32_e32 v147, v151, v151
	v_mul_f32_e32 v148, v153, v153
	v_fmac_f32_e32 v147, v150, v150
	v_fmac_f32_e32 v148, v152, v152
	v_add_f32_e32 v147, v147, v148
	v_mul_f32_e32 v148, v187, v187
	v_mul_f32_e32 v149, v185, v185
	v_fmac_f32_e32 v148, v186, v186
	v_fmac_f32_e32 v149, v184, v184
	v_add_f32_e32 v148, v148, v149
	v_add_f32_e32 v147, v147, v148
	v_add_f32_e32 v154, v146, v147
	v_cvt_pk_bf16_f32 v146, v150, v151
	v_cvt_pk_bf16_f32 v147, v152, v153
	v_cvt_pk_bf16_f32 v148, v186, v187
	v_cvt_pk_bf16_f32 v149, v184, v185
	global_store_dwordx4 v[202:203], v[146:149], off offset:256
	s_nop 1
	v_mov_b32_e32 v146, v1
	s_nop 1
	v_permlane16_swap_b32_e32 v1, v146
	v_add_f32_e32 v146, v1, v146
	v_mov_b32_e32 v1, v154
	s_nop 1
	v_permlane16_swap_b32_e32 v154, v1
	v_add_f32_e32 v147, v154, v1
	v_mov_b32_e32 v148, v146
	v_mov_b32_e32 v149, v147
	s_nop 0
	v_permlane32_swap_b32_e32 v146, v148
	v_permlane32_swap_b32_e32 v147, v149
	s_and_saveexec_b64 s[38:39], s[6:7]
	v_pk_add_f32 v[146:147], v[146:147], v[148:149]
	ds_write_b64 v182, v[146:147]
	s_or_b64 exec, exec, s[38:39]
	v_or_b32_e32 v184, 16, v174
	v_ashrrev_i32_e32 v185, 31, v184
	v_lshlrev_b64 v[146:147], 13, v[184:185]
	v_lshl_add_u64 v[146:147], s[14:15], 0, v[146:147]
	v_lshl_add_u64 v[158:159], v[172:173], 2, v[146:147]
	v_lshl_add_u64 v[146:147], v[184:185], 3, s[18:19]
	global_load_dwordx2 v[186:187], v[146:147], off
	s_nop 0
	global_load_dwordx4 v[146:149], v[158:159], off nt
	global_load_dwordx4 v[150:153], v[158:159], off offset:16 nt
	global_load_dwordx4 v[154:157], v[158:159], off offset:512 nt
	s_nop 0
	global_load_dwordx4 v[158:161], v[158:159], off offset:528 nt
	v_lshlrev_b64 v[184:185], 12, v[184:185]
	v_lshl_add_u64 v[184:185], s[16:17], 0, v[184:185]
	v_lshl_add_u64 v[184:185], v[172:173], 1, v[184:185]
	s_waitcnt vmcnt(3)
; #define PG8_LAS __attribute__((address_space(3)))
; __device__ __forceinline__ float bf_lo(unsigned w) { return __uint_as_float(w << 16); }
; __device__ __forceinline__ float bf_hi(unsigned w) { return __uint_as_float(w & 0xffff0000u); }
;     __device__ __forceinline__ void operator()(const f32x4 (&acc)[2][2][4][2], const Unit& u, int wr, int wc, int fr, int fq) const {
;     ...
;             for (int m = 0; m < MB; ++m) { const size_t ro = (size_t)(row0 + ai * HALF + (mb + m) * 16); ms[m] = *(const float2*)(must + ro * 2);
; #pragma unroll
;                 for (int bj = 0; bj < 2; ++bj) { const size_t o = ro * 2048 + col0 + bj * HALF;
;                     if (SRCF32) { xf[m][bj][0] = *(const f32x4*)((const float*)src + o); xf[m][bj][1] = *(const f32x4*)((const float*)src + o + 4); }
;                     else xb[m][bj] = *(const u32x4*)((const bf16_t*)src + o); } }
;             asm volatile("" ::: "memory");
; #pragma unroll
;             for (int m = 0; m < MB; ++m) { const size_t ro = (size_t)(row0 + ai * HALF + (mb + m) * 16); float s = 0.f, q = 0.f;
; #pragma unroll
;                 for (int bj = 0; bj < 2; ++bj) { const size_t o = ro * 2048 + col0 + bj * HALF; f32x4 x0, x1;
;                     if (SRCF32) { x0 = xf[m][bj][0]; x1 = xf[m][bj][1]; }
;                     else { const u32x4 w = xb[m][bj]; x0 = (f32x4){bf_lo(w.x), bf_hi(w.x), bf_lo(w.y), bf_hi(w.y)}; x1 = (f32x4){bf_lo(w.z), bf_hi(w.z), bf_lo(w.w), bf_hi(w.w)}; }
;                     x0 = (x0 - ms[m].x) * ms[m].y * gv[bj][0] + bv[bj][0]; x1 = (x1 - ms[m].x) * ms[m].y * gv[bj][1] + bv[bj][1];
;                     const f32x4 v0 = x0 * alpha + acc[ai][bj][mb + m][0], v1 = x1 * alpha + acc[ai][bj][mb + m][1];
;                     if (EMIT) { s += ((v0[0] + v0[1]) + (v0[2] + v0[3])) + ((v1[0] + v1[1]) + (v1[2] + v1[3]));
;                         q += ((v0[0] * v0[0] + v0[1] * v0[1]) + (v0[2] * v0[2] + v0[3] * v0[3])) + ((v1[0] * v1[0] + v1[1] * v1[1]) + (v1[2] * v1[2] + v1[3] * v1[3])); }
;                     *(u32x4*)(dst + o) = PG8_PACK8(v0, v1); }
;                 if (EMIT) { s = xsum16(s); s = xsum32(s); q = xsum16(q); q = xsum32(q);
;                     if (fq == 0) { PG8_LAS float* d = lred + ((ai * HALF + wr * 64 + (mb + m) * 16 + fr) * 4 + wc) * 2; d[0] = s; d[1] = q; } } }
	v_sub_f32_e32 v147, v147, v186
	v_sub_f32_e32 v146, v146, v186
	v_sub_f32_e32 v149, v149, v186
	v_sub_f32_e32 v148, v148, v186
	s_waitcnt vmcnt(2)
	v_sub_f32_e32 v151, v151, v186
	v_sub_f32_e32 v150, v150, v186
	v_sub_f32_e32 v153, v153, v186
	v_sub_f32_e32 v152, v152, v186
	s_waitcnt vmcnt(1)
	v_sub_f32_e32 v155, v155, v186
	v_sub_f32_e32 v154, v154, v186
	v_sub_f32_e32 v157, v157, v186
	v_sub_f32_e32 v156, v156, v186
	s_waitcnt vmcnt(0)
	v_sub_f32_e32 v159, v159, v186
	v_sub_f32_e32 v158, v158, v186
	v_sub_f32_e32 v161, v161, v186
	v_sub_f32_e32 v160, v160, v186
	v_pk_mul_f32 v[148:149], v[186:187], v[148:149] op_sel:[1,0]
	v_pk_mul_f32 v[146:147], v[186:187], v[146:147] op_sel:[1,0]
	v_pk_mul_f32 v[152:153], v[186:187], v[152:153] op_sel:[1,0]
	v_pk_mul_f32 v[150:151], v[186:187], v[150:151] op_sel:[1,0]
	v_pk_mul_f32 v[156:157], v[186:187], v[156:157] op_sel:[1,0]
	v_pk_mul_f32 v[154:155], v[186:187], v[154:155] op_sel:[1,0]
	v_pk_mul_f32 v[160:161], v[186:187], v[160:161] op_sel:[1,0]
	v_pk_mul_f32 v[158:159], v[186:187], v[158:159] op_sel:[1,0]
	v_pk_fma_f32 v[146:147], v[94:95], v[146:147], v[74:75]
	v_pk_fma_f32 v[148:149], v[96:97], v[148:149], v[76:77]
	v_pk_fma_f32 v[150:151], v[78:79], v[150:151], v[90:91]
	v_pk_fma_f32 v[152:153], v[80:81], v[152:153], v[92:93]
	v_pk_fma_f32 v[154:155], v[86:87], v[154:155], v[66:67]
	v_pk_fma_f32 v[156:157], v[88:89], v[156:157], v[68:69]
	v_pk_fma_f32 v[158:159], v[70:71], v[158:159], v[82:83]
	v_pk_fma_f32 v[160:161], v[72:73], v[160:161], v[84:85]
	v_pk_fma_f32 v[144:145], v[148:149], s[96:97], v[144:145] op_sel_hi:[1,0,1]
	v_pk_fma_f32 v[142:143], v[146:147], s[96:97], v[142:143] op_sel_hi:[1,0,1]
	v_pk_fma_f32 v[140:141], v[152:153], s[96:97], v[140:141] op_sel_hi:[1,0,1]
	v_pk_fma_f32 v[138:139], v[150:151], s[96:97], v[138:139] op_sel_hi:[1,0,1]
	v_pk_fma_f32 v[136:137], v[156:157], s[96:97], v[136:137] op_sel_hi:[1,0,1]
	v_pk_fma_f32 v[134:135], v[154:155], s[96:97], v[134:135] op_sel_hi:[1,0,1]
	v_pk_fma_f32 v[146:147], v[160:161], s[96:97], v[132:133] op_sel_hi:[1,0,1]
	v_pk_fma_f32 v[148:149], v[158:159], s[96:97], v[130:131] op_sel_hi:[1,0,1]
	v_add_f32_e32 v1, v142, v143
	v_add_f32_e32 v150, v144, v145
	v_add_f32_e32 v151, v138, v139
	v_add_f32_e32 v152, v140, v141
	v_mul_f32_e32 v153, v143, v143
	v_mul_f32_e32 v154, v145, v145
	v_mul_f32_e32 v155, v139, v139
	v_mul_f32_e32 v156, v141, v141
	v_cvt_pk_bf16_f32 v130, v142, v143
	v_cvt_pk_bf16_f32 v131, v144, v145
	v_cvt_pk_bf16_f32 v132, v138, v139
	v_cvt_pk_bf16_f32 v133, v140, v141
	v_add_f32_e32 v139, v134, v135
	v_add_f32_e32 v141, v136, v137
	v_add_f32_e32 v143, v148, v149
	v_add_f32_e32 v145, v146, v147
	v_add_f32_e32 v1, v1, v150
	v_add_f32_e32 v150, v151, v152
	global_store_dwordx4 v[184:185], v[130:133], off
	v_add_f32_e32 v1, v1, v150
	v_add_f32_e32 v1, 0, v1
	v_add_f32_e32 v130, v139, v141
	v_add_f32_e32 v131, v143, v145
	v_add_f32_e32 v130, v130, v131
	v_mul_f32_e32 v157, v135, v135
	v_mul_f32_e32 v158, v137, v137
	v_mul_f32_e32 v159, v149, v149
	v_add_f32_e32 v1, v130, v1
	v_mul_f32_e32 v130, v147, v147
	v_fmac_f32_e32 v153, v142, v142
	v_fmac_f32_e32 v154, v144, v144
	v_fmac_f32_e32 v155, v138, v138
	v_fmac_f32_e32 v156, v140, v140
	v_fmac_f32_e32 v157, v134, v134
	v_fmac_f32_e32 v158, v136, v136
	v_fmac_f32_e32 v159, v148, v148
	v_fmac_f32_e32 v130, v146, v146
	v_add_f32_e32 v132, v153, v154
	v_add_f32_e32 v133, v155, v156
	v_add_f32_e32 v131, v157, v158
	v_add_f32_e32 v130, v159, v130
	v_add_f32_e32 v132, v132, v133
	v_add_f32_e32 v130, v131, v130
	v_add_f32_e32 v138, v132, v130
	v_cvt_pk_bf16_f32 v130, v134, v135
	v_cvt_pk_bf16_f32 v131, v136, v137
	v_cvt_pk_bf16_f32 v132, v148, v149
	v_cvt_pk_bf16_f32 v133, v146, v147
	global_store_dwordx4 v[184:185], v[130:133], off offset:256
	s_nop 1
	v_mov_b32_e32 v130, v1
	s_nop 1
	v_permlane16_swap_b32_e32 v1, v130
	v_add_f32_e32 v130, v1, v130
	v_mov_b32_e32 v1, v138
	s_nop 1
	v_permlane16_swap_b32_e32 v138, v1
	v_add_f32_e32 v131, v138, v1
	v_mov_b32_e32 v132, v130
	v_mov_b32_e32 v133, v131
	s_nop 0
	v_permlane32_swap_b32_e32 v130, v132
	v_permlane32_swap_b32_e32 v131, v133
	s_and_saveexec_b64 s[38:39], s[6:7]
	v_pk_add_f32 v[130:131], v[130:131], v[132:133]
	ds_write_b64 v182, v[130:131] offset:512
	s_or_b64 exec, exec, s[38:39]
	v_or_b32_e32 v146, 32, v174
	v_ashrrev_i32_e32 v147, 31, v146
	v_lshlrev_b64 v[130:131], 13, v[146:147]
	v_lshl_add_u64 v[130:131], s[14:15], 0, v[130:131]
	v_lshl_add_u64 v[142:143], v[172:173], 2, v[130:131]
	v_lshl_add_u64 v[130:131], v[146:147], 3, s[18:19]
	global_load_dwordx2 v[148:149], v[130:131], off
	s_nop 0
	global_load_dwordx4 v[130:133], v[142:143], off nt
	global_load_dwordx4 v[134:137], v[142:143], off offset:16 nt
	global_load_dwordx4 v[138:141], v[142:143], off offset:512 nt
	s_nop 0
	global_load_dwordx4 v[142:145], v[142:143], off offset:528 nt
	v_lshlrev_b64 v[146:147], 12, v[146:147]
	v_lshl_add_u64 v[146:147], s[16:17], 0, v[146:147]
	v_lshl_add_u64 v[146:147], v[172:173], 1, v[146:147]
	s_waitcnt vmcnt(3)
	v_sub_f32_e32 v131, v131, v148
	v_sub_f32_e32 v130, v130, v148
	v_sub_f32_e32 v133, v133, v148
	v_sub_f32_e32 v132, v132, v148
	s_waitcnt vmcnt(2)
	v_sub_f32_e32 v135, v135, v148
	v_sub_f32_e32 v134, v134, v148
	v_sub_f32_e32 v137, v137, v148
	v_sub_f32_e32 v136, v136, v148
	s_waitcnt vmcnt(1)
	v_sub_f32_e32 v139, v139, v148
	v_sub_f32_e32 v138, v138, v148
	v_sub_f32_e32 v141, v141, v148
	v_sub_f32_e32 v140, v140, v148
	s_waitcnt vmcnt(0)
; #define PG8_LAS __attribute__((address_space(3)))
; __device__ __forceinline__ float bf_lo(unsigned w) { return __uint_as_float(w << 16); }
; __device__ __forceinline__ float bf_hi(unsigned w) { return __uint_as_float(w & 0xffff0000u); }
;     __device__ __forceinline__ void operator()(const f32x4 (&acc)[2][2][4][2], const Unit& u, int wr, int wc, int fr, int fq) const {
;     ...
;             for (int m = 0; m < MB; ++m) { const size_t ro = (size_t)(row0 + ai * HALF + (mb + m) * 16); ms[m] = *(const float2*)(must + ro * 2);
; #pragma unroll
;                 for (int bj = 0; bj < 2; ++bj) { const size_t o = ro * 2048 + col0 + bj * HALF;
;                     if (SRCF32) { xf[m][bj][0] = *(const f32x4*)((const float*)src + o); xf[m][bj][1] = *(const f32x4*)((const float*)src + o + 4); }
;                     else xb[m][bj] = *(const u32x4*)((const bf16_t*)src + o); } }
;             asm volatile("" ::: "memory");
; #pragma unroll
;             for (int m = 0; m < MB; ++m) { const size_t ro = (size_t)(row0 + ai * HALF + (mb + m) * 16); float s = 0.f, q = 0.f;
; #pragma unroll
;                 for (int bj = 0; bj < 2; ++bj) { const size_t o = ro * 2048 + col0 + bj * HALF; f32x4 x0, x1;
;                     if (SRCF32) { x0 = xf[m][bj][0]; x1 = xf[m][bj][1]; }
;                     else { const u32x4 w = xb[m][bj]; x0 = (f32x4){bf_lo(w.x), bf_hi(w.x), bf_lo(w.y), bf_hi(w.y)}; x1 = (f32x4){bf_lo(w.z), bf_hi(w.z), bf_lo(w.w), bf_hi(w.w)}; }
;                     x0 = (x0 - ms[m].x) * ms[m].y * gv[bj][0] + bv[bj][0]; x1 = (x1 - ms[m].x) * ms[m].y * gv[bj][1] + bv[bj][1];
;                     const f32x4 v0 = x0 * alpha + acc[ai][bj][mb + m][0], v1 = x1 * alpha + acc[ai][bj][mb + m][1];
;                     if (EMIT) { s += ((v0[0] + v0[1]) + (v0[2] + v0[3])) + ((v1[0] + v1[1]) + (v1[2] + v1[3]));
;                         q += ((v0[0] * v0[0] + v0[1] * v0[1]) + (v0[2] * v0[2] + v0[3] * v0[3])) + ((v1[0] * v1[0] + v1[1] * v1[1]) + (v1[2] * v1[2] + v1[3] * v1[3])); }
;                     *(u32x4*)(dst + o) = PG8_PACK8(v0, v1); }
;                 if (EMIT) { s = xsum16(s); s = xsum32(s); q = xsum16(q); q = xsum32(q);
;                     if (fq == 0) { PG8_LAS float* d = lred + ((ai * HALF + wr * 64 + (mb + m) * 16 + fr) * 4 + wc) * 2; d[0] = s; d[1] = q; } } }
	v_sub_f32_e32 v143, v143, v148
	v_sub_f32_e32 v142, v142, v148
	v_sub_f32_e32 v145, v145, v148
	v_sub_f32_e32 v144, v144, v148
	v_pk_mul_f32 v[132:133], v[148:149], v[132:133] op_sel:[1,0]
	v_pk_mul_f32 v[130:131], v[148:149], v[130:131] op_sel:[1,0]
	v_pk_mul_f32 v[136:137], v[148:149], v[136:137] op_sel:[1,0]
	v_pk_mul_f32 v[134:135], v[148:149], v[134:135] op_sel:[1,0]
	v_pk_mul_f32 v[140:141], v[148:149], v[140:141] op_sel:[1,0]
	v_pk_mul_f32 v[138:139], v[148:149], v[138:139] op_sel:[1,0]
	v_pk_mul_f32 v[144:145], v[148:149], v[144:145] op_sel:[1,0]
	v_pk_mul_f32 v[142:143], v[148:149], v[142:143] op_sel:[1,0]
	v_pk_fma_f32 v[130:131], v[94:95], v[130:131], v[74:75]
	v_pk_fma_f32 v[132:133], v[96:97], v[132:133], v[76:77]
	v_pk_fma_f32 v[134:135], v[78:79], v[134:135], v[90:91]
	v_pk_fma_f32 v[136:137], v[80:81], v[136:137], v[92:93]
	v_pk_fma_f32 v[138:139], v[86:87], v[138:139], v[66:67]
	v_pk_fma_f32 v[140:141], v[88:89], v[140:141], v[68:69]
	v_pk_fma_f32 v[142:143], v[70:71], v[142:143], v[82:83]
	v_pk_fma_f32 v[144:145], v[72:73], v[144:145], v[84:85]
	v_pk_fma_f32 v[128:129], v[132:133], s[96:97], v[128:129] op_sel_hi:[1,0,1]
	v_pk_fma_f32 v[126:127], v[130:131], s[96:97], v[126:127] op_sel_hi:[1,0,1]
	v_pk_fma_f32 v[124:125], v[136:137], s[96:97], v[124:125] op_sel_hi:[1,0,1]
	v_pk_fma_f32 v[122:123], v[134:135], s[96:97], v[122:123] op_sel_hi:[1,0,1]
	v_pk_fma_f32 v[120:121], v[140:141], s[96:97], v[120:121] op_sel_hi:[1,0,1]
	v_pk_fma_f32 v[118:119], v[138:139], s[96:97], v[118:119] op_sel_hi:[1,0,1]
	v_pk_fma_f32 v[130:131], v[144:145], s[96:97], v[116:117] op_sel_hi:[1,0,1]
	v_pk_fma_f32 v[132:133], v[142:143], s[96:97], v[114:115] op_sel_hi:[1,0,1]
	v_add_f32_e32 v1, v126, v127
	v_add_f32_e32 v134, v128, v129
	v_add_f32_e32 v135, v122, v123
	v_add_f32_e32 v136, v124, v125
	v_mul_f32_e32 v137, v127, v127
	v_mul_f32_e32 v138, v129, v129
	v_mul_f32_e32 v139, v123, v123
	v_mul_f32_e32 v140, v125, v125
	v_cvt_pk_bf16_f32 v114, v126, v127
	v_cvt_pk_bf16_f32 v115, v128, v129
	v_cvt_pk_bf16_f32 v116, v122, v123
	v_cvt_pk_bf16_f32 v117, v124, v125
	v_add_f32_e32 v123, v118, v119
	v_add_f32_e32 v125, v120, v121
	v_add_f32_e32 v127, v132, v133
	v_add_f32_e32 v129, v130, v131
	v_add_f32_e32 v1, v1, v134
	v_add_f32_e32 v134, v135, v136
	global_store_dwordx4 v[146:147], v[114:117], off
	v_add_f32_e32 v1, v1, v134
	v_add_f32_e32 v1, 0, v1
	v_add_f32_e32 v114, v123, v125
	v_add_f32_e32 v115, v127, v129
	v_add_f32_e32 v114, v114, v115
	v_mul_f32_e32 v141, v119, v119
	v_mul_f32_e32 v142, v121, v121
	v_mul_f32_e32 v143, v133, v133
	v_add_f32_e32 v1, v114, v1
	v_mul_f32_e32 v114, v131, v131
	v_fmac_f32_e32 v137, v126, v126
	v_fmac_f32_e32 v138, v128, v128
	v_fmac_f32_e32 v139, v122, v122
	v_fmac_f32_e32 v140, v124, v124
	v_fmac_f32_e32 v141, v118, v118
	v_fmac_f32_e32 v142, v120, v120
	v_fmac_f32_e32 v143, v132, v132
	v_fmac_f32_e32 v114, v130, v130
	v_add_f32_e32 v116, v137, v138
	v_add_f32_e32 v117, v139, v140
	v_add_f32_e32 v115, v141, v142
	v_add_f32_e32 v114, v143, v114
	v_add_f32_e32 v116, v116, v117
	v_add_f32_e32 v114, v115, v114
	v_add_f32_e32 v122, v116, v114
	v_cvt_pk_bf16_f32 v114, v118, v119
	v_cvt_pk_bf16_f32 v115, v120, v121
	v_cvt_pk_bf16_f32 v116, v132, v133
	v_cvt_pk_bf16_f32 v117, v130, v131
	global_store_dwordx4 v[146:147], v[114:117], off offset:256
	s_nop 1
	v_mov_b32_e32 v114, v1
	s_nop 1
	v_permlane16_swap_b32_e32 v1, v114
	v_add_f32_e32 v114, v1, v114
	v_mov_b32_e32 v1, v122
	s_nop 1
	v_permlane16_swap_b32_e32 v122, v1
	v_add_f32_e32 v115, v122, v1
	v_mov_b32_e32 v116, v114
	v_mov_b32_e32 v117, v115
	s_nop 0
	v_permlane32_swap_b32_e32 v114, v116
	v_permlane32_swap_b32_e32 v115, v117
	s_and_saveexec_b64 s[38:39], s[6:7]
	v_pk_add_f32 v[114:115], v[114:115], v[116:117]
	ds_write_b64 v182, v[114:115] offset:1024
	s_or_b64 exec, exec, s[38:39]
	v_or_b32_e32 v130, 48, v174
	v_ashrrev_i32_e32 v131, 31, v130
	v_lshlrev_b64 v[114:115], 13, v[130:131]
	v_lshl_add_u64 v[114:115], s[14:15], 0, v[114:115]
	v_lshl_add_u64 v[126:127], v[172:173], 2, v[114:115]
	v_lshl_add_u64 v[114:115], v[130:131], 3, s[18:19]
	global_load_dwordx2 v[132:133], v[114:115], off
	s_nop 0
	global_load_dwordx4 v[114:117], v[126:127], off nt
	global_load_dwordx4 v[118:121], v[126:127], off offset:16 nt
	global_load_dwordx4 v[122:125], v[126:127], off offset:512 nt
	s_nop 0
	global_load_dwordx4 v[126:129], v[126:127], off offset:528 nt
	v_lshlrev_b64 v[130:131], 12, v[130:131]
	v_lshl_add_u64 v[130:131], s[16:17], 0, v[130:131]
	v_lshl_add_u64 v[130:131], v[172:173], 1, v[130:131]
	s_waitcnt vmcnt(3)
	v_sub_f32_e32 v115, v115, v132
	v_sub_f32_e32 v114, v114, v132
	v_sub_f32_e32 v117, v117, v132
	v_sub_f32_e32 v116, v116, v132
	s_waitcnt vmcnt(2)
	v_sub_f32_e32 v119, v119, v132
	v_sub_f32_e32 v118, v118, v132
	v_sub_f32_e32 v121, v121, v132
	v_sub_f32_e32 v120, v120, v132
	s_waitcnt vmcnt(1)
	v_sub_f32_e32 v123, v123, v132
	v_sub_f32_e32 v122, v122, v132
	v_sub_f32_e32 v125, v125, v132
	v_sub_f32_e32 v124, v124, v132
	s_waitcnt vmcnt(0)
; #define PG8_LAS __attribute__((address_space(3)))
; __device__ __forceinline__ float bf_lo(unsigned w) { return __uint_as_float(w << 16); }
; __device__ __forceinline__ float bf_hi(unsigned w) { return __uint_as_float(w & 0xffff0000u); }
;     __device__ __forceinline__ void operator()(const f32x4 (&acc)[2][2][4][2], const Unit& u, int wr, int wc, int fr, int fq) const {
;     ...
;             for (int m = 0; m < MB; ++m) { const size_t ro = (size_t)(row0 + ai * HALF + (mb + m) * 16); ms[m] = *(const float2*)(must + ro * 2);
; #pragma unroll
;                 for (int bj = 0; bj < 2; ++bj) { const size_t o = ro * 2048 + col0 + bj * HALF;
;                     if (SRCF32) { xf[m][bj][0] = *(const f32x4*)((const float*)src + o); xf[m][bj][1] = *(const f32x4*)((const float*)src + o + 4); }
;                     else xb[m][bj] = *(const u32x4*)((const bf16_t*)src + o); } }
;             asm volatile("" ::: "memory");
; #pragma unroll
;             for (int m = 0; m < MB; ++m) { const size_t ro = (size_t)(row0 + ai * HALF + (mb + m) * 16); float s = 0.f, q = 0.f;
; #pragma unroll
;                 for (int bj = 0; bj < 2; ++bj) { const size_t o = ro * 2048 + col0 + bj * HALF; f32x4 x0, x1;
;                     if (SRCF32) { x0 = xf[m][bj][0]; x1 = xf[m][bj][1]; }
;                     else { const u32x4 w = xb[m][bj]; x0 = (f32x4){bf_lo(w.x), bf_hi(w.x), bf_lo(w.y), bf_hi(w.y)}; x1 = (f32x4){bf_lo(w.z), bf_hi(w.z), bf_lo(w.w), bf_hi(w.w)}; }
;                     x0 = (x0 - ms[m].x) * ms[m].y * gv[bj][0] + bv[bj][0]; x1 = (x1 - ms[m].x) * ms[m].y * gv[bj][1] + bv[bj][1];
;                     const f32x4 v0 = x0 * alpha + acc[ai][bj][mb + m][0], v1 = x1 * alpha + acc[ai][bj][mb + m][1];
;                     if (EMIT) { s += ((v0[0] + v0[1]) + (v0[2] + v0[3])) + ((v1[0] + v1[1]) + (v1[2] + v1[3]));
;                         q += ((v0[0] * v0[0] + v0[1] * v0[1]) + (v0[2] * v0[2] + v0[3] * v0[3])) + ((v1[0] * v1[0] + v1[1] * v1[1]) + (v1[2] * v1[2] + v1[3] * v1[3])); }
;                     *(u32x4*)(dst + o) = PG8_PACK8(v0, v1); }
;                 if (EMIT) { s = xsum16(s); s = xsum32(s); q = xsum16(q); q = xsum32(q);
;                     if (fq == 0) { PG8_LAS float* d = lred + ((ai * HALF + wr * 64 + (mb + m) * 16 + fr) * 4 + wc) * 2; d[0] = s; d[1] = q; } } }
	v_sub_f32_e32 v127, v127, v132
	v_sub_f32_e32 v126, v126, v132
	v_sub_f32_e32 v129, v129, v132
	v_sub_f32_e32 v128, v128, v132
	v_pk_mul_f32 v[116:117], v[132:133], v[116:117] op_sel:[1,0]
	v_pk_mul_f32 v[114:115], v[132:133], v[114:115] op_sel:[1,0]
	v_pk_mul_f32 v[120:121], v[132:133], v[120:121] op_sel:[1,0]
	v_pk_mul_f32 v[118:119], v[132:133], v[118:119] op_sel:[1,0]
	v_pk_mul_f32 v[124:125], v[132:133], v[124:125] op_sel:[1,0]
	v_pk_mul_f32 v[122:123], v[132:133], v[122:123] op_sel:[1,0]
	v_pk_mul_f32 v[128:129], v[132:133], v[128:129] op_sel:[1,0]
	v_pk_mul_f32 v[126:127], v[132:133], v[126:127] op_sel:[1,0]
	v_pk_fma_f32 v[114:115], v[94:95], v[114:115], v[74:75]
	v_pk_fma_f32 v[116:117], v[96:97], v[116:117], v[76:77]
	v_pk_fma_f32 v[118:119], v[78:79], v[118:119], v[90:91]
	v_pk_fma_f32 v[120:121], v[80:81], v[120:121], v[92:93]
	v_pk_fma_f32 v[122:123], v[86:87], v[122:123], v[66:67]
	v_pk_fma_f32 v[124:125], v[88:89], v[124:125], v[68:69]
	v_pk_fma_f32 v[126:127], v[70:71], v[126:127], v[82:83]
	v_pk_fma_f32 v[128:129], v[72:73], v[128:129], v[84:85]
	v_pk_fma_f32 v[112:113], v[116:117], s[96:97], v[112:113] op_sel_hi:[1,0,1]
	v_pk_fma_f32 v[110:111], v[114:115], s[96:97], v[110:111] op_sel_hi:[1,0,1]
	v_pk_fma_f32 v[108:109], v[120:121], s[96:97], v[108:109] op_sel_hi:[1,0,1]
	v_pk_fma_f32 v[106:107], v[118:119], s[96:97], v[106:107] op_sel_hi:[1,0,1]
	v_pk_fma_f32 v[104:105], v[124:125], s[96:97], v[104:105] op_sel_hi:[1,0,1]
	v_pk_fma_f32 v[102:103], v[122:123], s[96:97], v[102:103] op_sel_hi:[1,0,1]
	v_pk_fma_f32 v[114:115], v[128:129], s[96:97], v[100:101] op_sel_hi:[1,0,1]
	v_pk_fma_f32 v[116:117], v[126:127], s[96:97], v[98:99] op_sel_hi:[1,0,1]
	v_add_f32_e32 v1, v110, v111
	v_add_f32_e32 v118, v112, v113
	v_add_f32_e32 v119, v106, v107
	v_add_f32_e32 v120, v108, v109
	v_mul_f32_e32 v121, v111, v111
	v_mul_f32_e32 v122, v113, v113
	v_mul_f32_e32 v123, v107, v107
	v_mul_f32_e32 v124, v109, v109
	v_cvt_pk_bf16_f32 v98, v110, v111
	v_cvt_pk_bf16_f32 v99, v112, v113
	v_cvt_pk_bf16_f32 v100, v106, v107
	v_cvt_pk_bf16_f32 v101, v108, v109
	v_add_f32_e32 v107, v102, v103
	v_add_f32_e32 v109, v104, v105
	v_add_f32_e32 v111, v116, v117
	v_add_f32_e32 v113, v114, v115
	v_add_f32_e32 v1, v1, v118
	v_add_f32_e32 v118, v119, v120
	global_store_dwordx4 v[130:131], v[98:101], off
	v_add_f32_e32 v1, v1, v118
	v_add_f32_e32 v1, 0, v1
	v_add_f32_e32 v98, v107, v109
	v_add_f32_e32 v99, v111, v113
	v_add_f32_e32 v98, v98, v99
	v_mul_f32_e32 v125, v103, v103
	v_mul_f32_e32 v126, v105, v105
	v_mul_f32_e32 v127, v117, v117
	v_add_f32_e32 v1, v98, v1
	v_mul_f32_e32 v98, v115, v115
	v_fmac_f32_e32 v121, v110, v110
	v_fmac_f32_e32 v122, v112, v112
	v_fmac_f32_e32 v123, v106, v106
	v_fmac_f32_e32 v124, v108, v108
	v_fmac_f32_e32 v125, v102, v102
	v_fmac_f32_e32 v126, v104, v104
	v_fmac_f32_e32 v127, v116, v116
	v_fmac_f32_e32 v98, v114, v114
	v_add_f32_e32 v100, v121, v122
	v_add_f32_e32 v101, v123, v124
	v_add_f32_e32 v99, v125, v126
	v_add_f32_e32 v98, v127, v98
	v_add_f32_e32 v100, v100, v101
	v_add_f32_e32 v98, v99, v98
	v_add_f32_e32 v106, v100, v98
	v_cvt_pk_bf16_f32 v98, v102, v103
	v_cvt_pk_bf16_f32 v99, v104, v105
	v_cvt_pk_bf16_f32 v100, v116, v117
	v_cvt_pk_bf16_f32 v101, v114, v115
	global_store_dwordx4 v[130:131], v[98:101], off offset:256
	s_nop 1
	v_mov_b32_e32 v98, v1
	s_nop 1
	v_permlane16_swap_b32_e32 v1, v98
	v_add_f32_e32 v98, v1, v98
	v_mov_b32_e32 v1, v106
	s_nop 1
	v_permlane16_swap_b32_e32 v106, v1
	v_add_f32_e32 v99, v106, v1
	v_mov_b32_e32 v100, v98
	v_mov_b32_e32 v101, v99
	s_nop 0
	v_permlane32_swap_b32_e32 v98, v100
	v_permlane32_swap_b32_e32 v99, v101
	s_and_saveexec_b64 s[38:39], s[6:7]
	v_pk_add_f32 v[98:99], v[98:99], v[100:101]
	ds_write_b64 v182, v[98:99] offset:1536
	s_or_b64 exec, exec, s[38:39]
	v_add_u32_e32 v114, 0x80, v174
	v_ashrrev_i32_e32 v115, 31, v114
	v_lshlrev_b64 v[98:99], 13, v[114:115]
	v_lshl_add_u64 v[98:99], s[14:15], 0, v[98:99]
	v_lshl_add_u64 v[110:111], v[172:173], 2, v[98:99]
	v_lshl_add_u64 v[98:99], v[114:115], 3, s[18:19]
	global_load_dwordx2 v[116:117], v[98:99], off
	s_nop 0
	global_load_dwordx4 v[98:101], v[110:111], off nt
	global_load_dwordx4 v[102:105], v[110:111], off offset:16 nt
	global_load_dwordx4 v[106:109], v[110:111], off offset:512 nt
	s_nop 0
	global_load_dwordx4 v[110:113], v[110:111], off offset:528 nt
	v_lshlrev_b64 v[114:115], 12, v[114:115]
	v_lshl_add_u64 v[114:115], s[16:17], 0, v[114:115]
	v_lshl_add_u64 v[114:115], v[172:173], 1, v[114:115]
	s_waitcnt vmcnt(3)
	v_sub_f32_e32 v99, v99, v116
	v_sub_f32_e32 v98, v98, v116
	v_sub_f32_e32 v101, v101, v116
	v_sub_f32_e32 v100, v100, v116
	s_waitcnt vmcnt(2)
	v_sub_f32_e32 v103, v103, v116
	v_sub_f32_e32 v102, v102, v116
	v_sub_f32_e32 v105, v105, v116
	v_sub_f32_e32 v104, v104, v116
	s_waitcnt vmcnt(1)
	v_sub_f32_e32 v107, v107, v116
	v_sub_f32_e32 v106, v106, v116
	v_sub_f32_e32 v109, v109, v116
	v_sub_f32_e32 v108, v108, v116
	s_waitcnt vmcnt(0)
; #define PG8_LAS __attribute__((address_space(3)))
; __device__ __forceinline__ float bf_lo(unsigned w) { return __uint_as_float(w << 16); }
; __device__ __forceinline__ float bf_hi(unsigned w) { return __uint_as_float(w & 0xffff0000u); }
;     __device__ __forceinline__ void operator()(const f32x4 (&acc)[2][2][4][2], const Unit& u, int wr, int wc, int fr, int fq) const {
;     ...
;             for (int m = 0; m < MB; ++m) { const size_t ro = (size_t)(row0 + ai * HALF + (mb + m) * 16); ms[m] = *(const float2*)(must + ro * 2);
; #pragma unroll
;                 for (int bj = 0; bj < 2; ++bj) { const size_t o = ro * 2048 + col0 + bj * HALF;
;                     if (SRCF32) { xf[m][bj][0] = *(const f32x4*)((const float*)src + o); xf[m][bj][1] = *(const f32x4*)((const float*)src + o + 4); }
;                     else xb[m][bj] = *(const u32x4*)((const bf16_t*)src + o); } }
;             asm volatile("" ::: "memory");
; #pragma unroll
;             for (int m = 0; m < MB; ++m) { const size_t ro = (size_t)(row0 + ai * HALF + (mb + m) * 16); float s = 0.f, q = 0.f;
; #pragma unroll
;                 for (int bj = 0; bj < 2; ++bj) { const size_t o = ro * 2048 + col0 + bj * HALF; f32x4 x0, x1;
;                     if (SRCF32) { x0 = xf[m][bj][0]; x1 = xf[m][bj][1]; }
;                     else { const u32x4 w = xb[m][bj]; x0 = (f32x4){bf_lo(w.x), bf_hi(w.x), bf_lo(w.y), bf_hi(w.y)}; x1 = (f32x4){bf_lo(w.z), bf_hi(w.z), bf_lo(w.w), bf_hi(w.w)}; }
;                     x0 = (x0 - ms[m].x) * ms[m].y * gv[bj][0] + bv[bj][0]; x1 = (x1 - ms[m].x) * ms[m].y * gv[bj][1] + bv[bj][1];
;                     const f32x4 v0 = x0 * alpha + acc[ai][bj][mb + m][0], v1 = x1 * alpha + acc[ai][bj][mb + m][1];
;                     if (EMIT) { s += ((v0[0] + v0[1]) + (v0[2] + v0[3])) + ((v1[0] + v1[1]) + (v1[2] + v1[3]));
;                         q += ((v0[0] * v0[0] + v0[1] * v0[1]) + (v0[2] * v0[2] + v0[3] * v0[3])) + ((v1[0] * v1[0] + v1[1] * v1[1]) + (v1[2] * v1[2] + v1[3] * v1[3])); }
;                     *(u32x4*)(dst + o) = PG8_PACK8(v0, v1); }
;                 if (EMIT) { s = xsum16(s); s = xsum32(s); q = xsum16(q); q = xsum32(q);
;                     if (fq == 0) { PG8_LAS float* d = lred + ((ai * HALF + wr * 64 + (mb + m) * 16 + fr) * 4 + wc) * 2; d[0] = s; d[1] = q; } } }
	v_sub_f32_e32 v111, v111, v116
	v_sub_f32_e32 v110, v110, v116
	v_sub_f32_e32 v113, v113, v116
	v_sub_f32_e32 v112, v112, v116
	v_pk_mul_f32 v[100:101], v[116:117], v[100:101] op_sel:[1,0]
	v_pk_mul_f32 v[98:99], v[116:117], v[98:99] op_sel:[1,0]
	v_pk_mul_f32 v[104:105], v[116:117], v[104:105] op_sel:[1,0]
	v_pk_mul_f32 v[102:103], v[116:117], v[102:103] op_sel:[1,0]
	v_pk_mul_f32 v[108:109], v[116:117], v[108:109] op_sel:[1,0]
	v_pk_mul_f32 v[106:107], v[116:117], v[106:107] op_sel:[1,0]
	v_pk_mul_f32 v[112:113], v[116:117], v[112:113] op_sel:[1,0]
	v_pk_mul_f32 v[110:111], v[116:117], v[110:111] op_sel:[1,0]
	v_pk_fma_f32 v[98:99], v[94:95], v[98:99], v[74:75]
	v_pk_fma_f32 v[100:101], v[96:97], v[100:101], v[76:77]
	v_pk_fma_f32 v[102:103], v[78:79], v[102:103], v[90:91]
	v_pk_fma_f32 v[104:105], v[80:81], v[104:105], v[92:93]
	v_pk_fma_f32 v[106:107], v[86:87], v[106:107], v[66:67]
	v_pk_fma_f32 v[108:109], v[88:89], v[108:109], v[68:69]
	v_pk_fma_f32 v[110:111], v[70:71], v[110:111], v[82:83]
	v_pk_fma_f32 v[112:113], v[72:73], v[112:113], v[84:85]
	v_pk_fma_f32 v[64:65], v[100:101], s[96:97], v[64:65] op_sel_hi:[1,0,1]
	v_pk_fma_f32 v[62:63], v[98:99], s[96:97], v[62:63] op_sel_hi:[1,0,1]
	v_pk_fma_f32 v[60:61], v[104:105], s[96:97], v[60:61] op_sel_hi:[1,0,1]
	v_pk_fma_f32 v[58:59], v[102:103], s[96:97], v[58:59] op_sel_hi:[1,0,1]
	v_pk_fma_f32 v[56:57], v[108:109], s[96:97], v[56:57] op_sel_hi:[1,0,1]
	v_pk_fma_f32 v[54:55], v[106:107], s[96:97], v[54:55] op_sel_hi:[1,0,1]
	v_pk_fma_f32 v[98:99], v[112:113], s[96:97], v[52:53] op_sel_hi:[1,0,1]
	v_pk_fma_f32 v[100:101], v[110:111], s[96:97], v[50:51] op_sel_hi:[1,0,1]
	v_add_f32_e32 v1, v62, v63
	v_add_f32_e32 v102, v64, v65
	v_add_f32_e32 v103, v58, v59
	v_add_f32_e32 v104, v60, v61
	v_mul_f32_e32 v105, v63, v63
	v_mul_f32_e32 v106, v65, v65
	v_mul_f32_e32 v107, v59, v59
	v_mul_f32_e32 v108, v61, v61
	v_cvt_pk_bf16_f32 v50, v62, v63
	v_cvt_pk_bf16_f32 v51, v64, v65
	v_cvt_pk_bf16_f32 v52, v58, v59
	v_cvt_pk_bf16_f32 v53, v60, v61
	v_add_f32_e32 v59, v54, v55
	v_add_f32_e32 v61, v56, v57
	v_add_f32_e32 v63, v100, v101
	v_add_f32_e32 v65, v98, v99
	v_add_f32_e32 v1, v1, v102
	v_add_f32_e32 v102, v103, v104
	global_store_dwordx4 v[114:115], v[50:53], off
	v_add_f32_e32 v1, v1, v102
	v_add_f32_e32 v1, 0, v1
	v_add_f32_e32 v50, v59, v61
	v_add_f32_e32 v51, v63, v65
	v_add_f32_e32 v50, v50, v51
	v_mul_f32_e32 v109, v55, v55
	v_mul_f32_e32 v110, v57, v57
	v_mul_f32_e32 v111, v101, v101
	v_add_f32_e32 v1, v50, v1
	v_mul_f32_e32 v50, v99, v99
	v_fmac_f32_e32 v105, v62, v62
	v_fmac_f32_e32 v106, v64, v64
	v_fmac_f32_e32 v107, v58, v58
	v_fmac_f32_e32 v108, v60, v60
	v_fmac_f32_e32 v109, v54, v54
	v_fmac_f32_e32 v110, v56, v56
	v_fmac_f32_e32 v111, v100, v100
	v_fmac_f32_e32 v50, v98, v98
	v_add_f32_e32 v52, v105, v106
	v_add_f32_e32 v53, v107, v108
	v_add_f32_e32 v51, v109, v110
	v_add_f32_e32 v50, v111, v50
	v_add_f32_e32 v52, v52, v53
	v_add_f32_e32 v50, v51, v50
	v_add_f32_e32 v58, v52, v50
	v_cvt_pk_bf16_f32 v50, v54, v55
	v_cvt_pk_bf16_f32 v51, v56, v57
	v_cvt_pk_bf16_f32 v52, v100, v101
	v_cvt_pk_bf16_f32 v53, v98, v99
	global_store_dwordx4 v[114:115], v[50:53], off offset:256
	s_nop 1
	v_mov_b32_e32 v50, v1
	s_nop 1
	v_permlane16_swap_b32_e32 v1, v50
	v_add_f32_e32 v50, v1, v50
	v_mov_b32_e32 v1, v58
	s_nop 1
	v_permlane16_swap_b32_e32 v58, v1
	v_add_f32_e32 v51, v58, v1
	v_mov_b32_e32 v52, v50
	v_mov_b32_e32 v53, v51
	s_nop 0
	v_permlane32_swap_b32_e32 v50, v52
	v_permlane32_swap_b32_e32 v51, v53
	s_and_saveexec_b64 s[38:39], s[6:7]
	v_pk_add_f32 v[50:51], v[50:51], v[52:53]
	ds_write_b64 v182, v[50:51] offset:4096
	s_or_b64 exec, exec, s[38:39]
	v_add_u32_e32 v98, 0x90, v174
	v_ashrrev_i32_e32 v99, 31, v98
	v_lshlrev_b64 v[50:51], 13, v[98:99]
	v_lshl_add_u64 v[50:51], s[14:15], 0, v[50:51]
	v_lshl_add_u64 v[62:63], v[172:173], 2, v[50:51]
	v_lshl_add_u64 v[50:51], v[98:99], 3, s[18:19]
	global_load_dwordx2 v[100:101], v[50:51], off
	s_nop 0
	global_load_dwordx4 v[50:53], v[62:63], off nt
	global_load_dwordx4 v[54:57], v[62:63], off offset:16 nt
	global_load_dwordx4 v[58:61], v[62:63], off offset:512 nt
	s_nop 0
	global_load_dwordx4 v[62:65], v[62:63], off offset:528 nt
	v_lshlrev_b64 v[98:99], 12, v[98:99]
	v_lshl_add_u64 v[98:99], s[16:17], 0, v[98:99]
	v_lshl_add_u64 v[98:99], v[172:173], 1, v[98:99]
	s_waitcnt vmcnt(3)
	v_sub_f32_e32 v51, v51, v100
	v_sub_f32_e32 v50, v50, v100
	v_sub_f32_e32 v53, v53, v100
	v_sub_f32_e32 v52, v52, v100
	s_waitcnt vmcnt(2)
	v_sub_f32_e32 v55, v55, v100
	v_sub_f32_e32 v54, v54, v100
	v_sub_f32_e32 v57, v57, v100
	v_sub_f32_e32 v56, v56, v100
	s_waitcnt vmcnt(1)
	v_sub_f32_e32 v59, v59, v100
	v_sub_f32_e32 v58, v58, v100
	v_sub_f32_e32 v61, v61, v100
	v_sub_f32_e32 v60, v60, v100
	s_waitcnt vmcnt(0)
; #define PG8_LAS __attribute__((address_space(3)))
; __device__ __forceinline__ float bf_lo(unsigned w) { return __uint_as_float(w << 16); }
; __device__ __forceinline__ float bf_hi(unsigned w) { return __uint_as_float(w & 0xffff0000u); }
;     __device__ __forceinline__ void operator()(const f32x4 (&acc)[2][2][4][2], const Unit& u, int wr, int wc, int fr, int fq) const {
;     ...
;             for (int m = 0; m < MB; ++m) { const size_t ro = (size_t)(row0 + ai * HALF + (mb + m) * 16); ms[m] = *(const float2*)(must + ro * 2);
; #pragma unroll
;                 for (int bj = 0; bj < 2; ++bj) { const size_t o = ro * 2048 + col0 + bj * HALF;
;                     if (SRCF32) { xf[m][bj][0] = *(const f32x4*)((const float*)src + o); xf[m][bj][1] = *(const f32x4*)((const float*)src + o + 4); }
;                     else xb[m][bj] = *(const u32x4*)((const bf16_t*)src + o); } }
;             asm volatile("" ::: "memory");
; #pragma unroll
;             for (int m = 0; m < MB; ++m) { const size_t ro = (size_t)(row0 + ai * HALF + (mb + m) * 16); float s = 0.f, q = 0.f;
; #pragma unroll
;                 for (int bj = 0; bj < 2; ++bj) { const size_t o = ro * 2048 + col0 + bj * HALF; f32x4 x0, x1;
;                     if (SRCF32) { x0 = xf[m][bj][0]; x1 = xf[m][bj][1]; }
;                     else { const u32x4 w = xb[m][bj]; x0 = (f32x4){bf_lo(w.x), bf_hi(w.x), bf_lo(w.y), bf_hi(w.y)}; x1 = (f32x4){bf_lo(w.z), bf_hi(w.z), bf_lo(w.w), bf_hi(w.w)}; }
;                     x0 = (x0 - ms[m].x) * ms[m].y * gv[bj][0] + bv[bj][0]; x1 = (x1 - ms[m].x) * ms[m].y * gv[bj][1] + bv[bj][1];
;                     const f32x4 v0 = x0 * alpha + acc[ai][bj][mb + m][0], v1 = x1 * alpha + acc[ai][bj][mb + m][1];
;                     if (EMIT) { s += ((v0[0] + v0[1]) + (v0[2] + v0[3])) + ((v1[0] + v1[1]) + (v1[2] + v1[3]));
;                         q += ((v0[0] * v0[0] + v0[1] * v0[1]) + (v0[2] * v0[2] + v0[3] * v0[3])) + ((v1[0] * v1[0] + v1[1] * v1[1]) + (v1[2] * v1[2] + v1[3] * v1[3])); }
;                     *(u32x4*)(dst + o) = PG8_PACK8(v0, v1); }
;                 if (EMIT) { s = xsum16(s); s = xsum32(s); q = xsum16(q); q = xsum32(q);
;                     if (fq == 0) { PG8_LAS float* d = lred + ((ai * HALF + wr * 64 + (mb + m) * 16 + fr) * 4 + wc) * 2; d[0] = s; d[1] = q; } } }
	v_sub_f32_e32 v63, v63, v100
	v_sub_f32_e32 v62, v62, v100
	v_sub_f32_e32 v65, v65, v100
	v_sub_f32_e32 v64, v64, v100
	v_pk_mul_f32 v[52:53], v[100:101], v[52:53] op_sel:[1,0]
	v_pk_mul_f32 v[50:51], v[100:101], v[50:51] op_sel:[1,0]
	v_pk_mul_f32 v[56:57], v[100:101], v[56:57] op_sel:[1,0]
	v_pk_mul_f32 v[54:55], v[100:101], v[54:55] op_sel:[1,0]
	v_pk_mul_f32 v[60:61], v[100:101], v[60:61] op_sel:[1,0]
	v_pk_mul_f32 v[58:59], v[100:101], v[58:59] op_sel:[1,0]
	v_pk_mul_f32 v[64:65], v[100:101], v[64:65] op_sel:[1,0]
	v_pk_mul_f32 v[62:63], v[100:101], v[62:63] op_sel:[1,0]
	v_pk_fma_f32 v[50:51], v[94:95], v[50:51], v[74:75]
	v_pk_fma_f32 v[52:53], v[96:97], v[52:53], v[76:77]
	v_pk_fma_f32 v[54:55], v[78:79], v[54:55], v[90:91]
	v_pk_fma_f32 v[56:57], v[80:81], v[56:57], v[92:93]
	v_pk_fma_f32 v[58:59], v[86:87], v[58:59], v[66:67]
	v_pk_fma_f32 v[60:61], v[88:89], v[60:61], v[68:69]
	v_pk_fma_f32 v[62:63], v[70:71], v[62:63], v[82:83]
	v_pk_fma_f32 v[64:65], v[72:73], v[64:65], v[84:85]
	v_pk_fma_f32 v[48:49], v[52:53], s[96:97], v[48:49] op_sel_hi:[1,0,1]
	v_pk_fma_f32 v[46:47], v[50:51], s[96:97], v[46:47] op_sel_hi:[1,0,1]
	v_pk_fma_f32 v[44:45], v[56:57], s[96:97], v[44:45] op_sel_hi:[1,0,1]
	v_pk_fma_f32 v[42:43], v[54:55], s[96:97], v[42:43] op_sel_hi:[1,0,1]
	v_pk_fma_f32 v[40:41], v[60:61], s[96:97], v[40:41] op_sel_hi:[1,0,1]
	v_pk_fma_f32 v[38:39], v[58:59], s[96:97], v[38:39] op_sel_hi:[1,0,1]
	v_pk_fma_f32 v[50:51], v[64:65], s[96:97], v[36:37] op_sel_hi:[1,0,1]
	v_pk_fma_f32 v[52:53], v[62:63], s[96:97], v[34:35] op_sel_hi:[1,0,1]
	v_add_f32_e32 v1, v46, v47
	v_add_f32_e32 v54, v48, v49
	v_add_f32_e32 v55, v42, v43
	v_add_f32_e32 v56, v44, v45
	v_mul_f32_e32 v57, v47, v47
	v_mul_f32_e32 v58, v49, v49
	v_mul_f32_e32 v59, v43, v43
	v_mul_f32_e32 v60, v45, v45
	v_cvt_pk_bf16_f32 v34, v46, v47
	v_cvt_pk_bf16_f32 v35, v48, v49
	v_cvt_pk_bf16_f32 v36, v42, v43
	v_cvt_pk_bf16_f32 v37, v44, v45
	v_add_f32_e32 v43, v38, v39
	v_add_f32_e32 v45, v40, v41
	v_add_f32_e32 v47, v52, v53
	v_add_f32_e32 v49, v50, v51
	v_add_f32_e32 v1, v1, v54
	v_add_f32_e32 v54, v55, v56
	global_store_dwordx4 v[98:99], v[34:37], off
	v_add_f32_e32 v1, v1, v54
	v_add_f32_e32 v1, 0, v1
	v_add_f32_e32 v34, v43, v45
	v_add_f32_e32 v35, v47, v49
	v_add_f32_e32 v34, v34, v35
	v_mul_f32_e32 v61, v39, v39
	v_mul_f32_e32 v62, v41, v41
	v_mul_f32_e32 v63, v53, v53
	v_add_f32_e32 v1, v34, v1
	v_mul_f32_e32 v34, v51, v51
	v_fmac_f32_e32 v57, v46, v46
	v_fmac_f32_e32 v58, v48, v48
	v_fmac_f32_e32 v59, v42, v42
	v_fmac_f32_e32 v60, v44, v44
	v_fmac_f32_e32 v61, v38, v38
	v_fmac_f32_e32 v62, v40, v40
	v_fmac_f32_e32 v63, v52, v52
	v_fmac_f32_e32 v34, v50, v50
	v_add_f32_e32 v36, v57, v58
	v_add_f32_e32 v37, v59, v60
	v_add_f32_e32 v35, v61, v62
	v_add_f32_e32 v34, v63, v34
	v_add_f32_e32 v36, v36, v37
	v_add_f32_e32 v34, v35, v34
	v_add_f32_e32 v42, v36, v34
	v_cvt_pk_bf16_f32 v34, v38, v39
	v_cvt_pk_bf16_f32 v35, v40, v41
	v_cvt_pk_bf16_f32 v36, v52, v53
	v_cvt_pk_bf16_f32 v37, v50, v51
	global_store_dwordx4 v[98:99], v[34:37], off offset:256
	s_nop 1
	v_mov_b32_e32 v34, v1
	s_nop 1
	v_permlane16_swap_b32_e32 v1, v34
	v_add_f32_e32 v34, v1, v34
	v_mov_b32_e32 v1, v42
	s_nop 1
	v_permlane16_swap_b32_e32 v42, v1
	v_add_f32_e32 v35, v42, v1
	v_mov_b32_e32 v36, v34
	v_mov_b32_e32 v37, v35
	s_nop 0
	v_permlane32_swap_b32_e32 v34, v36
	v_permlane32_swap_b32_e32 v35, v37
	s_and_saveexec_b64 s[38:39], s[6:7]
	v_pk_add_f32 v[34:35], v[34:35], v[36:37]
	ds_write_b64 v182, v[34:35] offset:4608
	s_or_b64 exec, exec, s[38:39]
	v_add_u32_e32 v50, 0xa0, v174
	v_ashrrev_i32_e32 v51, 31, v50
	v_lshlrev_b64 v[34:35], 13, v[50:51]
	v_lshl_add_u64 v[34:35], s[14:15], 0, v[34:35]
	v_lshl_add_u64 v[46:47], v[172:173], 2, v[34:35]
	v_lshl_add_u64 v[34:35], v[50:51], 3, s[18:19]
	global_load_dwordx2 v[52:53], v[34:35], off
	s_nop 0
	global_load_dwordx4 v[34:37], v[46:47], off nt
	global_load_dwordx4 v[38:41], v[46:47], off offset:16 nt
	global_load_dwordx4 v[42:45], v[46:47], off offset:512 nt
	s_nop 0
	global_load_dwordx4 v[46:49], v[46:47], off offset:528 nt
	v_lshlrev_b64 v[50:51], 12, v[50:51]
	v_lshl_add_u64 v[50:51], s[16:17], 0, v[50:51]
	v_lshl_add_u64 v[50:51], v[172:173], 1, v[50:51]
	s_waitcnt vmcnt(3)
	v_sub_f32_e32 v35, v35, v52
	v_sub_f32_e32 v34, v34, v52
	v_sub_f32_e32 v37, v37, v52
	v_sub_f32_e32 v36, v36, v52
	s_waitcnt vmcnt(2)
	v_sub_f32_e32 v39, v39, v52
	v_sub_f32_e32 v38, v38, v52
	v_sub_f32_e32 v41, v41, v52
	v_sub_f32_e32 v40, v40, v52
	s_waitcnt vmcnt(1)
	v_sub_f32_e32 v43, v43, v52
	v_sub_f32_e32 v42, v42, v52
	v_sub_f32_e32 v45, v45, v52
	v_sub_f32_e32 v44, v44, v52
	s_waitcnt vmcnt(0)
; #define PG8_LAS __attribute__((address_space(3)))
; __device__ __forceinline__ float bf_lo(unsigned w) { return __uint_as_float(w << 16); }
; __device__ __forceinline__ float bf_hi(unsigned w) { return __uint_as_float(w & 0xffff0000u); }
;     __device__ __forceinline__ void operator()(const f32x4 (&acc)[2][2][4][2], const Unit& u, int wr, int wc, int fr, int fq) const {
;     ...
;             for (int m = 0; m < MB; ++m) { const size_t ro = (size_t)(row0 + ai * HALF + (mb + m) * 16); ms[m] = *(const float2*)(must + ro * 2);
; #pragma unroll
;                 for (int bj = 0; bj < 2; ++bj) { const size_t o = ro * 2048 + col0 + bj * HALF;
;                     if (SRCF32) { xf[m][bj][0] = *(const f32x4*)((const float*)src + o); xf[m][bj][1] = *(const f32x4*)((const float*)src + o + 4); }
;                     else xb[m][bj] = *(const u32x4*)((const bf16_t*)src + o); } }
;             asm volatile("" ::: "memory");
; #pragma unroll
;             for (int m = 0; m < MB; ++m) { const size_t ro = (size_t)(row0 + ai * HALF + (mb + m) * 16); float s = 0.f, q = 0.f;
; #pragma unroll
;                 for (int bj = 0; bj < 2; ++bj) { const size_t o = ro * 2048 + col0 + bj * HALF; f32x4 x0, x1;
;                     if (SRCF32) { x0 = xf[m][bj][0]; x1 = xf[m][bj][1]; }
;                     else { const u32x4 w = xb[m][bj]; x0 = (f32x4){bf_lo(w.x), bf_hi(w.x), bf_lo(w.y), bf_hi(w.y)}; x1 = (f32x4){bf_lo(w.z), bf_hi(w.z), bf_lo(w.w), bf_hi(w.w)}; }
;                     x0 = (x0 - ms[m].x) * ms[m].y * gv[bj][0] + bv[bj][0]; x1 = (x1 - ms[m].x) * ms[m].y * gv[bj][1] + bv[bj][1];
;                     const f32x4 v0 = x0 * alpha + acc[ai][bj][mb + m][0], v1 = x1 * alpha + acc[ai][bj][mb + m][1];
;                     if (EMIT) { s += ((v0[0] + v0[1]) + (v0[2] + v0[3])) + ((v1[0] + v1[1]) + (v1[2] + v1[3]));
;                         q += ((v0[0] * v0[0] + v0[1] * v0[1]) + (v0[2] * v0[2] + v0[3] * v0[3])) + ((v1[0] * v1[0] + v1[1] * v1[1]) + (v1[2] * v1[2] + v1[3] * v1[3])); }
;                     *(u32x4*)(dst + o) = PG8_PACK8(v0, v1); }
;                 if (EMIT) { s = xsum16(s); s = xsum32(s); q = xsum16(q); q = xsum32(q);
;                     if (fq == 0) { PG8_LAS float* d = lred + ((ai * HALF + wr * 64 + (mb + m) * 16 + fr) * 4 + wc) * 2; d[0] = s; d[1] = q; } } }
	v_sub_f32_e32 v47, v47, v52
	v_sub_f32_e32 v46, v46, v52
	v_sub_f32_e32 v49, v49, v52
	v_sub_f32_e32 v48, v48, v52
	v_pk_mul_f32 v[36:37], v[52:53], v[36:37] op_sel:[1,0]
	v_pk_mul_f32 v[34:35], v[52:53], v[34:35] op_sel:[1,0]
	v_pk_mul_f32 v[40:41], v[52:53], v[40:41] op_sel:[1,0]
	v_pk_mul_f32 v[38:39], v[52:53], v[38:39] op_sel:[1,0]
	v_pk_mul_f32 v[44:45], v[52:53], v[44:45] op_sel:[1,0]
	v_pk_mul_f32 v[42:43], v[52:53], v[42:43] op_sel:[1,0]
	v_pk_mul_f32 v[48:49], v[52:53], v[48:49] op_sel:[1,0]
	v_pk_mul_f32 v[46:47], v[52:53], v[46:47] op_sel:[1,0]
	v_pk_fma_f32 v[34:35], v[94:95], v[34:35], v[74:75]
	v_pk_fma_f32 v[36:37], v[96:97], v[36:37], v[76:77]
	v_pk_fma_f32 v[38:39], v[78:79], v[38:39], v[90:91]
	v_pk_fma_f32 v[40:41], v[80:81], v[40:41], v[92:93]
	v_pk_fma_f32 v[42:43], v[86:87], v[42:43], v[66:67]
	v_pk_fma_f32 v[44:45], v[88:89], v[44:45], v[68:69]
	v_pk_fma_f32 v[46:47], v[70:71], v[46:47], v[82:83]
	v_pk_fma_f32 v[48:49], v[72:73], v[48:49], v[84:85]
	v_pk_fma_f32 v[32:33], v[36:37], s[96:97], v[32:33] op_sel_hi:[1,0,1]
	v_pk_fma_f32 v[30:31], v[34:35], s[96:97], v[30:31] op_sel_hi:[1,0,1]
	v_pk_fma_f32 v[28:29], v[40:41], s[96:97], v[28:29] op_sel_hi:[1,0,1]
	v_pk_fma_f32 v[26:27], v[38:39], s[96:97], v[26:27] op_sel_hi:[1,0,1]
	v_pk_fma_f32 v[24:25], v[44:45], s[96:97], v[24:25] op_sel_hi:[1,0,1]
	v_pk_fma_f32 v[22:23], v[42:43], s[96:97], v[22:23] op_sel_hi:[1,0,1]
	v_pk_fma_f32 v[34:35], v[48:49], s[96:97], v[20:21] op_sel_hi:[1,0,1]
	v_pk_fma_f32 v[36:37], v[46:47], s[96:97], v[18:19] op_sel_hi:[1,0,1]
	v_add_f32_e32 v1, v30, v31
	v_add_f32_e32 v38, v32, v33
	v_add_f32_e32 v39, v26, v27
	v_add_f32_e32 v40, v28, v29
	v_mul_f32_e32 v41, v31, v31
	v_mul_f32_e32 v42, v33, v33
	v_mul_f32_e32 v43, v27, v27
	v_mul_f32_e32 v44, v29, v29
	v_cvt_pk_bf16_f32 v18, v30, v31
	v_cvt_pk_bf16_f32 v19, v32, v33
	v_cvt_pk_bf16_f32 v20, v26, v27
	v_cvt_pk_bf16_f32 v21, v28, v29
	v_add_f32_e32 v27, v22, v23
	v_add_f32_e32 v29, v24, v25
	v_add_f32_e32 v31, v36, v37
	v_add_f32_e32 v33, v34, v35
	v_add_f32_e32 v1, v1, v38
	v_add_f32_e32 v38, v39, v40
	global_store_dwordx4 v[50:51], v[18:21], off
	v_add_f32_e32 v1, v1, v38
	v_add_f32_e32 v1, 0, v1
	v_add_f32_e32 v18, v27, v29
	v_add_f32_e32 v19, v31, v33
	v_add_f32_e32 v18, v18, v19
	v_mul_f32_e32 v45, v23, v23
	v_mul_f32_e32 v46, v25, v25
	v_mul_f32_e32 v47, v37, v37
	v_add_f32_e32 v1, v18, v1
	v_mul_f32_e32 v18, v35, v35
	v_fmac_f32_e32 v41, v30, v30
	v_fmac_f32_e32 v42, v32, v32
	v_fmac_f32_e32 v43, v26, v26
	v_fmac_f32_e32 v44, v28, v28
	v_fmac_f32_e32 v45, v22, v22
	v_fmac_f32_e32 v46, v24, v24
	v_fmac_f32_e32 v47, v36, v36
	v_fmac_f32_e32 v18, v34, v34
	v_add_f32_e32 v20, v41, v42
	v_add_f32_e32 v21, v43, v44
	v_add_f32_e32 v19, v45, v46
	v_add_f32_e32 v18, v47, v18
	v_add_f32_e32 v20, v20, v21
	v_add_f32_e32 v18, v19, v18
	v_add_f32_e32 v26, v20, v18
	v_cvt_pk_bf16_f32 v18, v22, v23
	v_cvt_pk_bf16_f32 v19, v24, v25
	v_cvt_pk_bf16_f32 v20, v36, v37
	v_cvt_pk_bf16_f32 v21, v34, v35
	global_store_dwordx4 v[50:51], v[18:21], off offset:256
	s_nop 1
	v_mov_b32_e32 v18, v1
	s_nop 1
	v_permlane16_swap_b32_e32 v1, v18
	v_add_f32_e32 v18, v1, v18
	v_mov_b32_e32 v1, v26
	s_nop 1
	v_permlane16_swap_b32_e32 v26, v1
	v_add_f32_e32 v19, v26, v1
	v_mov_b32_e32 v20, v18
	v_mov_b32_e32 v21, v19
	s_nop 0
	v_permlane32_swap_b32_e32 v18, v20
	v_permlane32_swap_b32_e32 v19, v21
	s_and_saveexec_b64 s[38:39], s[6:7]
	v_pk_add_f32 v[18:19], v[18:19], v[20:21]
	ds_write_b64 v182, v[18:19] offset:5120
	s_or_b64 exec, exec, s[38:39]
	v_add_u32_e32 v34, 0xb0, v174
	v_ashrrev_i32_e32 v35, 31, v34
	v_lshlrev_b64 v[18:19], 13, v[34:35]
	v_lshl_add_u64 v[18:19], s[14:15], 0, v[18:19]
	v_lshl_add_u64 v[30:31], v[172:173], 2, v[18:19]
	v_lshl_add_u64 v[18:19], v[34:35], 3, s[18:19]
	global_load_dwordx2 v[36:37], v[18:19], off
	s_nop 0
	global_load_dwordx4 v[18:21], v[30:31], off nt
	global_load_dwordx4 v[22:25], v[30:31], off offset:16 nt
	global_load_dwordx4 v[26:29], v[30:31], off offset:512 nt
	s_nop 0
	global_load_dwordx4 v[30:33], v[30:31], off offset:528 nt
	v_lshlrev_b64 v[34:35], 12, v[34:35]
	v_lshl_add_u64 v[34:35], s[16:17], 0, v[34:35]
	v_lshl_add_u64 v[34:35], v[172:173], 1, v[34:35]
	s_waitcnt vmcnt(3)
	v_sub_f32_e32 v19, v19, v36
	v_sub_f32_e32 v18, v18, v36
	v_sub_f32_e32 v21, v21, v36
	v_sub_f32_e32 v20, v20, v36
	s_waitcnt vmcnt(2)
; #define PG8_LAS __attribute__((address_space(3)))
; __device__ __forceinline__ float bf_lo(unsigned w) { return __uint_as_float(w << 16); }
; __device__ __forceinline__ float bf_hi(unsigned w) { return __uint_as_float(w & 0xffff0000u); }
;     __device__ __forceinline__ void operator()(const f32x4 (&acc)[2][2][4][2], const Unit& u, int wr, int wc, int fr, int fq) const {
;     ...
;             for (int m = 0; m < MB; ++m) { const size_t ro = (size_t)(row0 + ai * HALF + (mb + m) * 16); float s = 0.f, q = 0.f;
; #pragma unroll
;                 for (int bj = 0; bj < 2; ++bj) { const size_t o = ro * 2048 + col0 + bj * HALF; f32x4 x0, x1;
;                     if (SRCF32) { x0 = xf[m][bj][0]; x1 = xf[m][bj][1]; }
;                     else { const u32x4 w = xb[m][bj]; x0 = (f32x4){bf_lo(w.x), bf_hi(w.x), bf_lo(w.y), bf_hi(w.y)}; x1 = (f32x4){bf_lo(w.z), bf_hi(w.z), bf_lo(w.w), bf_hi(w.w)}; }
;                     x0 = (x0 - ms[m].x) * ms[m].y * gv[bj][0] + bv[bj][0]; x1 = (x1 - ms[m].x) * ms[m].y * gv[bj][1] + bv[bj][1];
;                     const f32x4 v0 = x0 * alpha + acc[ai][bj][mb + m][0], v1 = x1 * alpha + acc[ai][bj][mb + m][1];
;                     if (EMIT) { s += ((v0[0] + v0[1]) + (v0[2] + v0[3])) + ((v1[0] + v1[1]) + (v1[2] + v1[3]));
;                         q += ((v0[0] * v0[0] + v0[1] * v0[1]) + (v0[2] * v0[2] + v0[3] * v0[3])) + ((v1[0] * v1[0] + v1[1] * v1[1]) + (v1[2] * v1[2] + v1[3] * v1[3])); }
;                     *(u32x4*)(dst + o) = PG8_PACK8(v0, v1); }
;                 if (EMIT) { s = xsum16(s); s = xsum32(s); q = xsum16(q); q = xsum32(q);
;                     if (fq == 0) { PG8_LAS float* d = lred + ((ai * HALF + wr * 64 + (mb + m) * 16 + fr) * 4 + wc) * 2; d[0] = s; d[1] = q; } } }
;             asm volatile("" ::: "memory"); }
;         if (EMIT) {
;             asm volatile("s_waitcnt lgkmcnt(0)" ::: "memory"); __builtin_amdgcn_s_barrier(); asm volatile("" ::: "memory");
;             const int t = (wr * 4 + wc) * 64 + fq * 16 + fr;
;             if (t < 256) { const PG8_LAS f32x4* d = (const PG8_LAS f32x4*)(lred + t * 8); const f32x4 a = d[0], b = d[1];
;                 float2 o2; o2.x = (a[0] + a[2]) + (b[0] + b[2]); o2.y = (a[1] + a[3]) + (b[1] + b[3]);
;                 *(float2*)(statp + ((size_t)(u.pm * BM + t) * 8 + u.pn) * 2) = o2; }
	v_sub_f32_e32 v23, v23, v36
	v_sub_f32_e32 v22, v22, v36
	v_sub_f32_e32 v25, v25, v36
	v_sub_f32_e32 v24, v24, v36
	s_waitcnt vmcnt(1)
	v_sub_f32_e32 v27, v27, v36
	v_sub_f32_e32 v26, v26, v36
	v_sub_f32_e32 v29, v29, v36
	v_sub_f32_e32 v28, v28, v36
	s_waitcnt vmcnt(0)
	v_sub_f32_e32 v31, v31, v36
	v_sub_f32_e32 v30, v30, v36
	v_sub_f32_e32 v33, v33, v36
	v_sub_f32_e32 v32, v32, v36
	v_pk_mul_f32 v[20:21], v[36:37], v[20:21] op_sel:[1,0]
	v_pk_mul_f32 v[18:19], v[36:37], v[18:19] op_sel:[1,0]
	v_pk_mul_f32 v[24:25], v[36:37], v[24:25] op_sel:[1,0]
	v_pk_mul_f32 v[22:23], v[36:37], v[22:23] op_sel:[1,0]
	v_pk_mul_f32 v[28:29], v[36:37], v[28:29] op_sel:[1,0]
	v_pk_mul_f32 v[26:27], v[36:37], v[26:27] op_sel:[1,0]
	v_pk_mul_f32 v[32:33], v[36:37], v[32:33] op_sel:[1,0]
	v_pk_mul_f32 v[30:31], v[36:37], v[30:31] op_sel:[1,0]
	v_pk_fma_f32 v[18:19], v[94:95], v[18:19], v[74:75]
	v_pk_fma_f32 v[20:21], v[96:97], v[20:21], v[76:77]
	v_pk_fma_f32 v[22:23], v[78:79], v[22:23], v[90:91]
	v_pk_fma_f32 v[24:25], v[80:81], v[24:25], v[92:93]
	v_pk_fma_f32 v[26:27], v[86:87], v[26:27], v[66:67]
	v_pk_fma_f32 v[28:29], v[88:89], v[28:29], v[68:69]
	v_pk_fma_f32 v[30:31], v[70:71], v[30:31], v[82:83]
	v_pk_fma_f32 v[32:33], v[72:73], v[32:33], v[84:85]
	v_pk_fma_f32 v[16:17], v[20:21], s[96:97], v[16:17] op_sel_hi:[1,0,1]
	v_pk_fma_f32 v[14:15], v[18:19], s[96:97], v[14:15] op_sel_hi:[1,0,1]
	v_pk_fma_f32 v[12:13], v[24:25], s[96:97], v[12:13] op_sel_hi:[1,0,1]
	v_pk_fma_f32 v[10:11], v[22:23], s[96:97], v[10:11] op_sel_hi:[1,0,1]
	v_pk_fma_f32 v[8:9], v[28:29], s[96:97], v[8:9] op_sel_hi:[1,0,1]
	v_pk_fma_f32 v[6:7], v[26:27], s[96:97], v[6:7] op_sel_hi:[1,0,1]
	v_pk_fma_f32 v[18:19], v[32:33], s[96:97], v[4:5] op_sel_hi:[1,0,1]
	v_pk_fma_f32 v[20:21], v[30:31], s[96:97], v[2:3] op_sel_hi:[1,0,1]
	v_add_f32_e32 v1, v14, v15
	v_add_f32_e32 v22, v16, v17
	v_add_f32_e32 v23, v10, v11
	v_add_f32_e32 v24, v12, v13
	v_mul_f32_e32 v25, v15, v15
	v_mul_f32_e32 v26, v17, v17
	v_mul_f32_e32 v27, v11, v11
	v_mul_f32_e32 v28, v13, v13
	v_cvt_pk_bf16_f32 v2, v14, v15
	v_cvt_pk_bf16_f32 v3, v16, v17
	v_cvt_pk_bf16_f32 v4, v10, v11
	v_cvt_pk_bf16_f32 v5, v12, v13
	v_add_f32_e32 v11, v6, v7
	v_add_f32_e32 v13, v8, v9
	v_add_f32_e32 v15, v20, v21
	v_add_f32_e32 v17, v18, v19
	v_add_f32_e32 v1, v1, v22
	v_add_f32_e32 v22, v23, v24
	global_store_dwordx4 v[34:35], v[2:5], off
	v_add_f32_e32 v1, v1, v22
	v_add_f32_e32 v1, 0, v1
	v_add_f32_e32 v2, v11, v13
	v_add_f32_e32 v3, v15, v17
	v_add_f32_e32 v2, v2, v3
	v_mul_f32_e32 v29, v7, v7
	v_mul_f32_e32 v30, v9, v9
	v_mul_f32_e32 v31, v21, v21
	v_add_f32_e32 v1, v2, v1
	v_mul_f32_e32 v2, v19, v19
	v_fmac_f32_e32 v25, v14, v14
	v_fmac_f32_e32 v26, v16, v16
	v_fmac_f32_e32 v27, v10, v10
	v_fmac_f32_e32 v28, v12, v12
	v_fmac_f32_e32 v29, v6, v6
	v_fmac_f32_e32 v30, v8, v8
	v_fmac_f32_e32 v31, v20, v20
	v_fmac_f32_e32 v2, v18, v18
	v_add_f32_e32 v4, v25, v26
	v_add_f32_e32 v5, v27, v28
	v_add_f32_e32 v3, v29, v30
	v_add_f32_e32 v2, v31, v2
	v_add_f32_e32 v4, v4, v5
	v_add_f32_e32 v2, v3, v2
	v_add_f32_e32 v10, v4, v2
	v_cvt_pk_bf16_f32 v2, v6, v7
	v_cvt_pk_bf16_f32 v3, v8, v9
	v_cvt_pk_bf16_f32 v4, v20, v21
	v_cvt_pk_bf16_f32 v5, v18, v19
	global_store_dwordx4 v[34:35], v[2:5], off offset:256
	s_nop 1
	v_mov_b32_e32 v2, v1
	s_nop 1
	v_permlane16_swap_b32_e32 v1, v2
	v_add_f32_e32 v2, v1, v2
	v_mov_b32_e32 v1, v10
	s_nop 1
	v_permlane16_swap_b32_e32 v10, v1
	v_add_f32_e32 v3, v10, v1
	v_mov_b32_e32 v4, v2
	v_mov_b32_e32 v5, v3
	s_nop 0
	v_permlane32_swap_b32_e32 v2, v4
	v_permlane32_swap_b32_e32 v3, v5
	s_and_saveexec_b64 s[38:39], s[6:7]
	v_pk_add_f32 v[2:3], v[2:3], v[4:5]
	ds_write_b64 v182, v[2:3] offset:5632
	s_or_b64 exec, exec, s[38:39]
	s_waitcnt lgkmcnt(0)
	s_barrier
	s_and_saveexec_b64 s[38:39], s[8:9]
	s_cbranch_execz .LBB0_888
	ds_read_b128 v[2:5], v181
	ds_read_b128 v[6:9], v181 offset:16
	v_add_u32_e32 v10, s31, v179
	v_ashrrev_i32_e32 v11, 31, v10
	v_lshlrev_b64 v[10:11], 6, v[10:11]
	s_ashr_i32 s31, s30, 31
	v_lshl_add_u64 v[10:11], s[24:25], 0, v[10:11]
	s_waitcnt lgkmcnt(1)
	v_pk_add_f32 v[2:3], v[2:3], v[4:5]
	s_waitcnt lgkmcnt(0)
	v_pk_add_f32 v[4:5], v[6:7], v[8:9]
	v_lshl_add_u64 v[10:11], s[30:31], 3, v[10:11]
	v_pk_add_f32 v[2:3], v[2:3], v[4:5]
	global_store_dwordx2 v[10:11], v[2:3], off
